# nt policy also on the f32 residual stores (EP_RES X stores, final_rows output stores): not re-read for hundreds of us / never
# speedup vs baseline: 1.0074x; 1.0031x over previous
; __device__ __forceinline__ unsigned cvt_pk_bf16(float lo, float hi) { f32x2 v = {lo, hi}; bf16x2_t b = __builtin_convertvector(v, bf16x2_t); return __builtin_bit_cast(unsigned, b); }
; template <int MODE> __device__ __forceinline__ void gemm_epilogue(f32x4 (&acc)[2][2][4][2], const GD& g, const pg8::Unit& u, int wr, int wc, int fr, int fq, LAS unsigned char* lds, const float (&rsv)[2][4]) {
;     const int rt = u.pm * 256 + wr * 64 + fr;
;     const int ct = wc * 32 + 8 * fq;
;     ...
;         const float* base = g.f0; float* out = (float*)g.o0; bf16_t* xb = (bf16_t*)g.o1; float* ssq = (float*)g.f1;
;         const int col0 = u.pn * 256 + wc * 32 + 4 * fq; const int rz = (u.z / g.nz2) * g.ro1;
; #pragma unroll
;         for (int ai = 0; ai < 2; ++ai)
; #pragma unroll
;             for (int m = 0; m < 4; ++m) { const size_t off = (size_t)(rz + rt + ai * 128 + m * 16) * DM + col0;
;                 float ss = 0.f;
; #pragma unroll
;                 for (int bj = 0; bj < 2; ++bj)
; #pragma unroll
;                     for (int n = 0; n < 2; ++n) { const f32x4 bs = *(const f32x4*)(base + off + bj * 128 + n * 16); const f32x4 y = bs + acc[ai][bj][m][n]; *(f32x4*)(out + off + bj * 128 + n * 16) = y;
;                         ss += (y[0] * y[0] + y[1] * y[1]) + (y[2] * y[2] + y[3] * y[3]);
;                         u32x2 w; w.x = cvt_pk_bf16(y[0], y[1]); w.y = cvt_pk_bf16(y[2], y[3]); if (xb) *(u32x2*)(xb + off + bj * 128 + n * 16) = w; }
;                 ss += __shfl_xor(ss, 16); ss += __shfl_xor(ss, 32);
;                 if (fq == 0) __hip_atomic_fetch_add(ssq + rz + rt + ai * 128 + m * 16, ss, __ATOMIC_RELAXED, __HIP_MEMORY_SCOPE_AGENT); }
.LBB0_196:
	s_abs_i32 s3, s38
	s_mul_hi_u32 s8, s3, s0
	s_mul_i32 s9, s8, s1
	s_ashr_i32 s2, s38, 31
	s_sub_i32 s3, s3, s9
	s_xor_b32 s2, s2, s52
	s_add_i32 s9, s8, 1
	s_sub_i32 s12, s3, s1
	s_cmp_ge_u32 s3, s1
	s_cselect_b32 s8, s9, s8
	s_cselect_b32 s3, s12, s3
	s_add_i32 s9, s8, 1
	s_cmp_ge_u32 s3, s1
	s_cselect_b32 s3, s9, s8
	s_xor_b32 s3, s3, s2
	s_sub_i32 s2, s3, s2
	v_readlane_b32 s3, v254, 59
	v_readlane_b32 s8, v254, 42
	v_lshl_add_u32 v144, s56, 8, v154
	s_mul_i32 s2, s2, s3
	v_readlane_b32 s9, v254, 43
	v_add_u32_e32 v144, s2, v144
	v_lshl_or_b32 v145, s53, 8, v164
	v_readlane_b32 s2, v254, 48
	v_readlane_b32 s3, v254, 49
	v_lshlrev_b32_e32 v146, 2, v144
	v_lshl_add_u32 v143, v144, 11, v145
	v_and_b32_e32 v149, 64, v252
	v_lshlrev_b32_e32 v147, 1, v143
	v_lshlrev_b32_e32 v143, 2, v143
	v_xor_b32_e32 v1, 16, v252
	v_add_u32_e32 v149, 64, v149
	v_xor_b32_e32 v142, 32, v252
	v_mov_b32_e32 v148, v143
	v_cmp_lt_i32_e32 vcc, v1, v149
	s_nop 1
	v_cndmask_b32_e32 v1, v252, v1, vcc
	v_cmp_lt_i32_e32 vcc, v142, v149
	v_lshlrev_b32_e32 v1, 2, v1
	s_nop 0
	v_cndmask_b32_e32 v142, v252, v142, vcc
	v_lshlrev_b32_e32 v142, 2, v142
	s_and_b64 vcc, exec, s[62:63]
	s_cbranch_vccz .Lres_noxb
	global_load_dwordx4 v[168:171], v143, s[2:3] offset:0 nt
	global_load_dwordx4 v[172:175], v143, s[2:3] offset:64 nt
	global_load_dwordx4 v[176:179], v143, s[2:3] offset:512 nt
	global_load_dwordx4 v[180:183], v143, s[2:3] offset:576 nt
	v_add_u32_e32 v143, 0x20000, v143
	global_load_dwordx4 v[184:187], v143, s[2:3] offset:0 nt
	global_load_dwordx4 v[188:191], v143, s[2:3] offset:64 nt
	global_load_dwordx4 v[196:199], v143, s[2:3] offset:512 nt
	global_load_dwordx4 v[204:207], v143, s[2:3] offset:576 nt
	v_add_u32_e32 v143, 0x20000, v143
	global_load_dwordx4 v[220:223], v143, s[2:3] offset:0 nt
	global_load_dwordx4 v[224:227], v143, s[2:3] offset:64 nt
	global_load_dwordx4 v[228:231], v143, s[2:3] offset:512 nt
	global_load_dwordx4 v[232:235], v143, s[2:3] offset:576 nt
	s_waitcnt vmcnt(8)
	v_pk_add_f32 v[128:129], v[128:129], v[170:171]
	v_pk_add_f32 v[126:127], v[126:127], v[168:169]
	v_pk_add_f32 v[124:125], v[124:125], v[174:175]
	v_pk_add_f32 v[122:123], v[122:123], v[172:173]
	v_pk_add_f32 v[120:121], v[120:121], v[178:179]
	v_pk_add_f32 v[118:119], v[118:119], v[176:177]
	v_pk_add_f32 v[116:117], v[116:117], v[182:183]
	v_pk_add_f32 v[114:115], v[114:115], v[180:181]
	global_store_dwordx4 v148, v[126:129], s[8:9] offset:0 nt
	global_store_dwordx4 v148, v[122:125], s[8:9] offset:64 nt
	global_store_dwordx4 v148, v[118:121], s[8:9] offset:512 nt
	global_store_dwordx4 v148, v[114:117], s[8:9] offset:576 nt
	v_cvt_pk_bf16_f32 v168, v126, v127
	v_cvt_pk_bf16_f32 v169, v128, v129
	v_cvt_pk_bf16_f32 v172, v122, v123
	v_cvt_pk_bf16_f32 v173, v124, v125
	v_cvt_pk_bf16_f32 v176, v118, v119
	v_cvt_pk_bf16_f32 v177, v120, v121
	v_cvt_pk_bf16_f32 v180, v114, v115
	v_cvt_pk_bf16_f32 v181, v116, v117
	global_store_dwordx2 v147, v[168:169], s[36:37] offset:0
	global_store_dwordx2 v147, v[172:173], s[36:37] offset:32
	global_store_dwordx2 v147, v[176:177], s[36:37] offset:256
	global_store_dwordx2 v147, v[180:181], s[36:37] offset:288
	v_mul_f32_e32 v150, v127, v127
	v_mul_f32_e32 v151, v129, v129
	v_fmac_f32_e32 v150, v126, v126
	v_fmac_f32_e32 v151, v128, v128
	v_add_f32_e32 v150, v150, v151
	v_mul_f32_e32 v152, v123, v123
	v_mul_f32_e32 v153, v125, v125
	v_fmac_f32_e32 v152, v122, v122
	v_fmac_f32_e32 v153, v124, v124
	v_add_f32_e32 v152, v152, v153
	v_add_f32_e32 v150, v150, v152
	v_mul_f32_e32 v152, v119, v119
	v_mul_f32_e32 v153, v121, v121
	v_fmac_f32_e32 v152, v118, v118
	v_fmac_f32_e32 v153, v120, v120
	v_add_f32_e32 v152, v152, v153
	v_add_f32_e32 v150, v150, v152
	v_mul_f32_e32 v152, v115, v115
	v_mul_f32_e32 v153, v117, v117
	v_fmac_f32_e32 v152, v114, v114
	v_fmac_f32_e32 v153, v116, v116
	v_add_f32_e32 v152, v152, v153
	v_add_f32_e32 v150, v150, v152
	ds_bpermute_b32 v192, v1, v150
	v_add_u32_e32 v143, 0x20000, v143
	global_load_dwordx4 v[168:171], v143, s[2:3] offset:0 nt
	global_load_dwordx4 v[172:175], v143, s[2:3] offset:64 nt
	global_load_dwordx4 v[176:179], v143, s[2:3] offset:512 nt
	global_load_dwordx4 v[180:183], v143, s[2:3] offset:576 nt
	s_waitcnt lgkmcnt(0)
	v_add_f32_e32 v150, v150, v192
	ds_bpermute_b32 v192, v142, v150
	v_add_u32_e32 v148, 0x20000, v148
	v_add_u32_e32 v147, 0x10000, v147
	s_and_saveexec_b64 s[12:13], s[6:7]
	s_waitcnt lgkmcnt(0)
	v_add_f32_e32 v150, v150, v192
	global_atomic_add_f32 v146, v150, s[70:71] offset:0
	s_mov_b64 exec, s[12:13]
	s_waitcnt vmcnt(17)
; __device__ __forceinline__ unsigned cvt_pk_bf16(float lo, float hi) { f32x2 v = {lo, hi}; bf16x2_t b = __builtin_convertvector(v, bf16x2_t); return __builtin_bit_cast(unsigned, b); }
; template <int MODE> __device__ __forceinline__ void gemm_epilogue(f32x4 (&acc)[2][2][4][2], const GD& g, const pg8::Unit& u, int wr, int wc, int fr, int fq, LAS unsigned char* lds, const float (&rsv)[2][4]) {
;     ...
;         const float* base = g.f0; float* out = (float*)g.o0; bf16_t* xb = (bf16_t*)g.o1; float* ssq = (float*)g.f1;
;         const int col0 = u.pn * 256 + wc * 32 + 4 * fq; const int rz = (u.z / g.nz2) * g.ro1;
; #pragma unroll
;         for (int ai = 0; ai < 2; ++ai)
; #pragma unroll
;             for (int m = 0; m < 4; ++m) { const size_t off = (size_t)(rz + rt + ai * 128 + m * 16) * DM + col0;
;                 float ss = 0.f;
; #pragma unroll
;                 for (int bj = 0; bj < 2; ++bj)
; #pragma unroll
;                     for (int n = 0; n < 2; ++n) { const f32x4 bs = *(const f32x4*)(base + off + bj * 128 + n * 16); const f32x4 y = bs + acc[ai][bj][m][n]; *(f32x4*)(out + off + bj * 128 + n * 16) = y;
;                         ss += (y[0] * y[0] + y[1] * y[1]) + (y[2] * y[2] + y[3] * y[3]);
;                         u32x2 w; w.x = cvt_pk_bf16(y[0], y[1]); w.y = cvt_pk_bf16(y[2], y[3]); if (xb) *(u32x2*)(xb + off + bj * 128 + n * 16) = w; }
;                 ss += __shfl_xor(ss, 16); ss += __shfl_xor(ss, 32);
;                 if (fq == 0) __hip_atomic_fetch_add(ssq + rz + rt + ai * 128 + m * 16, ss, __ATOMIC_RELAXED, __HIP_MEMORY_SCOPE_AGENT); }
	v_pk_add_f32 v[112:113], v[112:113], v[186:187]
	v_pk_add_f32 v[110:111], v[110:111], v[184:185]
	v_pk_add_f32 v[108:109], v[108:109], v[190:191]
	v_pk_add_f32 v[106:107], v[106:107], v[188:189]
	v_pk_add_f32 v[104:105], v[104:105], v[198:199]
	v_pk_add_f32 v[102:103], v[102:103], v[196:197]
	v_pk_add_f32 v[100:101], v[100:101], v[206:207]
	v_pk_add_f32 v[98:99], v[98:99], v[204:205]
	global_store_dwordx4 v148, v[110:113], s[8:9] offset:0 nt
	global_store_dwordx4 v148, v[106:109], s[8:9] offset:64 nt
	global_store_dwordx4 v148, v[102:105], s[8:9] offset:512 nt
	global_store_dwordx4 v148, v[98:101], s[8:9] offset:576 nt
	v_cvt_pk_bf16_f32 v184, v110, v111
	v_cvt_pk_bf16_f32 v185, v112, v113
	v_cvt_pk_bf16_f32 v188, v106, v107
	v_cvt_pk_bf16_f32 v189, v108, v109
	v_cvt_pk_bf16_f32 v196, v102, v103
	v_cvt_pk_bf16_f32 v197, v104, v105
	v_cvt_pk_bf16_f32 v204, v98, v99
	v_cvt_pk_bf16_f32 v205, v100, v101
	global_store_dwordx2 v147, v[184:185], s[36:37] offset:0
	global_store_dwordx2 v147, v[188:189], s[36:37] offset:32
	global_store_dwordx2 v147, v[196:197], s[36:37] offset:256
	global_store_dwordx2 v147, v[204:205], s[36:37] offset:288
	v_mul_f32_e32 v150, v111, v111
	v_mul_f32_e32 v151, v113, v113
	v_fmac_f32_e32 v150, v110, v110
	v_fmac_f32_e32 v151, v112, v112
	v_add_f32_e32 v150, v150, v151
	v_mul_f32_e32 v152, v107, v107
	v_mul_f32_e32 v153, v109, v109
	v_fmac_f32_e32 v152, v106, v106
	v_fmac_f32_e32 v153, v108, v108
	v_add_f32_e32 v152, v152, v153
	v_add_f32_e32 v150, v150, v152
	v_mul_f32_e32 v152, v103, v103
	v_mul_f32_e32 v153, v105, v105
	v_fmac_f32_e32 v152, v102, v102
	v_fmac_f32_e32 v153, v104, v104
	v_add_f32_e32 v152, v152, v153
	v_add_f32_e32 v150, v150, v152
	v_mul_f32_e32 v152, v99, v99
	v_mul_f32_e32 v153, v101, v101
	v_fmac_f32_e32 v152, v98, v98
	v_fmac_f32_e32 v153, v100, v100
	v_add_f32_e32 v152, v152, v153
	v_add_f32_e32 v150, v150, v152
	ds_bpermute_b32 v192, v1, v150
	v_add_u32_e32 v143, 0xa0000, v143
	global_load_dwordx4 v[184:187], v143, s[2:3] offset:0 nt
	global_load_dwordx4 v[188:191], v143, s[2:3] offset:64 nt
	global_load_dwordx4 v[196:199], v143, s[2:3] offset:512 nt
	global_load_dwordx4 v[204:207], v143, s[2:3] offset:576 nt
	s_waitcnt lgkmcnt(0)
	v_add_f32_e32 v150, v150, v192
	ds_bpermute_b32 v192, v142, v150
	v_add_u32_e32 v148, 0x20000, v148
	v_add_u32_e32 v147, 0x10000, v147
	s_and_saveexec_b64 s[12:13], s[6:7]
	s_waitcnt lgkmcnt(0)
	v_add_f32_e32 v150, v150, v192
	global_atomic_add_f32 v146, v150, s[70:71] offset:64
	s_mov_b64 exec, s[12:13]
	s_waitcnt vmcnt(26)
	v_pk_add_f32 v[96:97], v[96:97], v[222:223]
	v_pk_add_f32 v[94:95], v[94:95], v[220:221]
	v_pk_add_f32 v[92:93], v[92:93], v[226:227]
	v_pk_add_f32 v[90:91], v[90:91], v[224:225]
	v_pk_add_f32 v[88:89], v[88:89], v[230:231]
	v_pk_add_f32 v[86:87], v[86:87], v[228:229]
	v_pk_add_f32 v[84:85], v[84:85], v[234:235]
	v_pk_add_f32 v[82:83], v[82:83], v[232:233]
	global_store_dwordx4 v148, v[94:97], s[8:9] offset:0 nt
	global_store_dwordx4 v148, v[90:93], s[8:9] offset:64 nt
	global_store_dwordx4 v148, v[86:89], s[8:9] offset:512 nt
	global_store_dwordx4 v148, v[82:85], s[8:9] offset:576 nt
	v_cvt_pk_bf16_f32 v220, v94, v95
	v_cvt_pk_bf16_f32 v221, v96, v97
	v_cvt_pk_bf16_f32 v224, v90, v91
	v_cvt_pk_bf16_f32 v225, v92, v93
	v_cvt_pk_bf16_f32 v228, v86, v87
	v_cvt_pk_bf16_f32 v229, v88, v89
	v_cvt_pk_bf16_f32 v232, v82, v83
	v_cvt_pk_bf16_f32 v233, v84, v85
	global_store_dwordx2 v147, v[220:221], s[36:37] offset:0
	global_store_dwordx2 v147, v[224:225], s[36:37] offset:32
	global_store_dwordx2 v147, v[228:229], s[36:37] offset:256
	global_store_dwordx2 v147, v[232:233], s[36:37] offset:288
	v_mul_f32_e32 v150, v95, v95
	v_mul_f32_e32 v151, v97, v97
	v_fmac_f32_e32 v150, v94, v94
	v_fmac_f32_e32 v151, v96, v96
	v_add_f32_e32 v150, v150, v151
	v_mul_f32_e32 v152, v91, v91
	v_mul_f32_e32 v153, v93, v93
	v_fmac_f32_e32 v152, v90, v90
	v_fmac_f32_e32 v153, v92, v92
	v_add_f32_e32 v152, v152, v153
	v_add_f32_e32 v150, v150, v152
	v_mul_f32_e32 v152, v87, v87
	v_mul_f32_e32 v153, v89, v89
	v_fmac_f32_e32 v152, v86, v86
	v_fmac_f32_e32 v153, v88, v88
	v_add_f32_e32 v152, v152, v153
	v_add_f32_e32 v150, v150, v152
	v_mul_f32_e32 v152, v83, v83
	v_mul_f32_e32 v153, v85, v85
	v_fmac_f32_e32 v152, v82, v82
	v_fmac_f32_e32 v153, v84, v84
	v_add_f32_e32 v152, v152, v153
	v_add_f32_e32 v150, v150, v152
	ds_bpermute_b32 v192, v1, v150
	v_add_u32_e32 v143, 0x20000, v143
	global_load_dwordx4 v[220:223], v143, s[2:3] offset:0 nt
	global_load_dwordx4 v[224:227], v143, s[2:3] offset:64 nt
	global_load_dwordx4 v[228:231], v143, s[2:3] offset:512 nt
	global_load_dwordx4 v[232:235], v143, s[2:3] offset:576 nt
	s_waitcnt lgkmcnt(0)
	v_add_f32_e32 v150, v150, v192
	ds_bpermute_b32 v192, v142, v150
	v_add_u32_e32 v148, 0x20000, v148
	v_add_u32_e32 v147, 0x10000, v147
	s_and_saveexec_b64 s[12:13], s[6:7]
	s_waitcnt lgkmcnt(0)
	v_add_f32_e32 v150, v150, v192
	global_atomic_add_f32 v146, v150, s[70:71] offset:128
	s_mov_b64 exec, s[12:13]
	s_waitcnt vmcnt(27)
; __device__ __forceinline__ unsigned cvt_pk_bf16(float lo, float hi) { f32x2 v = {lo, hi}; bf16x2_t b = __builtin_convertvector(v, bf16x2_t); return __builtin_bit_cast(unsigned, b); }
; template <int MODE> __device__ __forceinline__ void gemm_epilogue(f32x4 (&acc)[2][2][4][2], const GD& g, const pg8::Unit& u, int wr, int wc, int fr, int fq, LAS unsigned char* lds, const float (&rsv)[2][4]) {
;     ...
;         const float* base = g.f0; float* out = (float*)g.o0; bf16_t* xb = (bf16_t*)g.o1; float* ssq = (float*)g.f1;
;         const int col0 = u.pn * 256 + wc * 32 + 4 * fq; const int rz = (u.z / g.nz2) * g.ro1;
; #pragma unroll
;         for (int ai = 0; ai < 2; ++ai)
; #pragma unroll
;             for (int m = 0; m < 4; ++m) { const size_t off = (size_t)(rz + rt + ai * 128 + m * 16) * DM + col0;
;                 float ss = 0.f;
; #pragma unroll
;                 for (int bj = 0; bj < 2; ++bj)
; #pragma unroll
;                     for (int n = 0; n < 2; ++n) { const f32x4 bs = *(const f32x4*)(base + off + bj * 128 + n * 16); const f32x4 y = bs + acc[ai][bj][m][n]; *(f32x4*)(out + off + bj * 128 + n * 16) = y;
;                         ss += (y[0] * y[0] + y[1] * y[1]) + (y[2] * y[2] + y[3] * y[3]);
;                         u32x2 w; w.x = cvt_pk_bf16(y[0], y[1]); w.y = cvt_pk_bf16(y[2], y[3]); if (xb) *(u32x2*)(xb + off + bj * 128 + n * 16) = w; }
;                 ss += __shfl_xor(ss, 16); ss += __shfl_xor(ss, 32);
;                 if (fq == 0) __hip_atomic_fetch_add(ssq + rz + rt + ai * 128 + m * 16, ss, __ATOMIC_RELAXED, __HIP_MEMORY_SCOPE_AGENT); }
	v_pk_add_f32 v[80:81], v[80:81], v[170:171]
	v_pk_add_f32 v[78:79], v[78:79], v[168:169]
	v_pk_add_f32 v[76:77], v[76:77], v[174:175]
	v_pk_add_f32 v[74:75], v[74:75], v[172:173]
	v_pk_add_f32 v[72:73], v[72:73], v[178:179]
	v_pk_add_f32 v[70:71], v[70:71], v[176:177]
	v_pk_add_f32 v[68:69], v[68:69], v[182:183]
	v_pk_add_f32 v[66:67], v[66:67], v[180:181]
	global_store_dwordx4 v148, v[78:81], s[8:9] offset:0 nt
	global_store_dwordx4 v148, v[74:77], s[8:9] offset:64 nt
	global_store_dwordx4 v148, v[70:73], s[8:9] offset:512 nt
	global_store_dwordx4 v148, v[66:69], s[8:9] offset:576 nt
	v_cvt_pk_bf16_f32 v168, v78, v79
	v_cvt_pk_bf16_f32 v169, v80, v81
	v_cvt_pk_bf16_f32 v172, v74, v75
	v_cvt_pk_bf16_f32 v173, v76, v77
	v_cvt_pk_bf16_f32 v176, v70, v71
	v_cvt_pk_bf16_f32 v177, v72, v73
	v_cvt_pk_bf16_f32 v180, v66, v67
	v_cvt_pk_bf16_f32 v181, v68, v69
	global_store_dwordx2 v147, v[168:169], s[36:37] offset:0
	global_store_dwordx2 v147, v[172:173], s[36:37] offset:32
	global_store_dwordx2 v147, v[176:177], s[36:37] offset:256
	global_store_dwordx2 v147, v[180:181], s[36:37] offset:288
	v_mul_f32_e32 v150, v79, v79
	v_mul_f32_e32 v151, v81, v81
	v_fmac_f32_e32 v150, v78, v78
	v_fmac_f32_e32 v151, v80, v80
	v_add_f32_e32 v150, v150, v151
	v_mul_f32_e32 v152, v75, v75
	v_mul_f32_e32 v153, v77, v77
	v_fmac_f32_e32 v152, v74, v74
	v_fmac_f32_e32 v153, v76, v76
	v_add_f32_e32 v152, v152, v153
	v_add_f32_e32 v150, v150, v152
	v_mul_f32_e32 v152, v71, v71
	v_mul_f32_e32 v153, v73, v73
	v_fmac_f32_e32 v152, v70, v70
	v_fmac_f32_e32 v153, v72, v72
	v_add_f32_e32 v152, v152, v153
	v_add_f32_e32 v150, v150, v152
	v_mul_f32_e32 v152, v67, v67
	v_mul_f32_e32 v153, v69, v69
	v_fmac_f32_e32 v152, v66, v66
	v_fmac_f32_e32 v153, v68, v68
	v_add_f32_e32 v152, v152, v153
	v_add_f32_e32 v150, v150, v152
	ds_bpermute_b32 v192, v1, v150
	v_add_u32_e32 v143, 0x20000, v143
	global_load_dwordx4 v[168:171], v143, s[2:3] offset:0 nt
	global_load_dwordx4 v[172:175], v143, s[2:3] offset:64 nt
	global_load_dwordx4 v[176:179], v143, s[2:3] offset:512 nt
	global_load_dwordx4 v[180:183], v143, s[2:3] offset:576 nt
	s_waitcnt lgkmcnt(0)
	v_add_f32_e32 v150, v150, v192
	ds_bpermute_b32 v192, v142, v150
	v_add_u32_e32 v148, 0xa0000, v148
	v_add_u32_e32 v147, 0x50000, v147
	s_and_saveexec_b64 s[12:13], s[6:7]
	s_waitcnt lgkmcnt(0)
	v_add_f32_e32 v150, v150, v192
	global_atomic_add_f32 v146, v150, s[70:71] offset:192
	s_mov_b64 exec, s[12:13]
	s_waitcnt vmcnt(27)
	v_pk_add_f32 v[64:65], v[64:65], v[186:187]
	v_pk_add_f32 v[62:63], v[62:63], v[184:185]
	v_pk_add_f32 v[60:61], v[60:61], v[190:191]
	v_pk_add_f32 v[58:59], v[58:59], v[188:189]
	v_pk_add_f32 v[56:57], v[56:57], v[198:199]
	v_pk_add_f32 v[54:55], v[54:55], v[196:197]
	v_pk_add_f32 v[52:53], v[52:53], v[206:207]
	v_pk_add_f32 v[50:51], v[50:51], v[204:205]
	global_store_dwordx4 v148, v[62:65], s[8:9] offset:0 nt
	global_store_dwordx4 v148, v[58:61], s[8:9] offset:64 nt
	global_store_dwordx4 v148, v[54:57], s[8:9] offset:512 nt
	global_store_dwordx4 v148, v[50:53], s[8:9] offset:576 nt
	v_cvt_pk_bf16_f32 v184, v62, v63
	v_cvt_pk_bf16_f32 v185, v64, v65
	v_cvt_pk_bf16_f32 v188, v58, v59
	v_cvt_pk_bf16_f32 v189, v60, v61
	v_cvt_pk_bf16_f32 v196, v54, v55
	v_cvt_pk_bf16_f32 v197, v56, v57
	v_cvt_pk_bf16_f32 v204, v50, v51
	v_cvt_pk_bf16_f32 v205, v52, v53
	global_store_dwordx2 v147, v[184:185], s[36:37] offset:0
	global_store_dwordx2 v147, v[188:189], s[36:37] offset:32
	global_store_dwordx2 v147, v[196:197], s[36:37] offset:256
	global_store_dwordx2 v147, v[204:205], s[36:37] offset:288
	v_mul_f32_e32 v150, v63, v63
	v_mul_f32_e32 v151, v65, v65
	v_fmac_f32_e32 v150, v62, v62
	v_fmac_f32_e32 v151, v64, v64
	v_add_f32_e32 v150, v150, v151
	v_mul_f32_e32 v152, v59, v59
	v_mul_f32_e32 v153, v61, v61
	v_fmac_f32_e32 v152, v58, v58
	v_fmac_f32_e32 v153, v60, v60
	v_add_f32_e32 v152, v152, v153
	v_add_f32_e32 v150, v150, v152
	v_mul_f32_e32 v152, v55, v55
	v_mul_f32_e32 v153, v57, v57
	v_fmac_f32_e32 v152, v54, v54
	v_fmac_f32_e32 v153, v56, v56
	v_add_f32_e32 v152, v152, v153
	v_add_f32_e32 v150, v150, v152
	v_mul_f32_e32 v152, v51, v51
	v_mul_f32_e32 v153, v53, v53
	v_fmac_f32_e32 v152, v50, v50
	v_fmac_f32_e32 v153, v52, v52
	v_add_f32_e32 v152, v152, v153
	v_add_f32_e32 v150, v150, v152
	ds_bpermute_b32 v192, v1, v150
	v_add_u32_e32 v143, 0x20000, v143
	global_load_dwordx4 v[184:187], v143, s[2:3] offset:0 nt
	global_load_dwordx4 v[188:191], v143, s[2:3] offset:64 nt
	global_load_dwordx4 v[196:199], v143, s[2:3] offset:512 nt
	global_load_dwordx4 v[204:207], v143, s[2:3] offset:576 nt
	s_waitcnt lgkmcnt(0)
	v_add_f32_e32 v150, v150, v192
	ds_bpermute_b32 v192, v142, v150
	v_add_u32_e32 v148, 0x20000, v148
	v_add_u32_e32 v147, 0x10000, v147
	s_and_saveexec_b64 s[12:13], s[6:7]
	s_waitcnt lgkmcnt(0)
	v_add_f32_e32 v150, v150, v192
	global_atomic_add_f32 v146, v150, s[70:71] offset:512
	s_mov_b64 exec, s[12:13]
	s_waitcnt vmcnt(27)
; __device__ __forceinline__ unsigned cvt_pk_bf16(float lo, float hi) { f32x2 v = {lo, hi}; bf16x2_t b = __builtin_convertvector(v, bf16x2_t); return __builtin_bit_cast(unsigned, b); }
; template <int MODE> __device__ __forceinline__ void gemm_epilogue(f32x4 (&acc)[2][2][4][2], const GD& g, const pg8::Unit& u, int wr, int wc, int fr, int fq, LAS unsigned char* lds, const float (&rsv)[2][4]) {
;     ...
;         const float* base = g.f0; float* out = (float*)g.o0; bf16_t* xb = (bf16_t*)g.o1; float* ssq = (float*)g.f1;
;         const int col0 = u.pn * 256 + wc * 32 + 4 * fq; const int rz = (u.z / g.nz2) * g.ro1;
; #pragma unroll
;         for (int ai = 0; ai < 2; ++ai)
; #pragma unroll
;             for (int m = 0; m < 4; ++m) { const size_t off = (size_t)(rz + rt + ai * 128 + m * 16) * DM + col0;
;                 float ss = 0.f;
; #pragma unroll
;                 for (int bj = 0; bj < 2; ++bj)
; #pragma unroll
;                     for (int n = 0; n < 2; ++n) { const f32x4 bs = *(const f32x4*)(base + off + bj * 128 + n * 16); const f32x4 y = bs + acc[ai][bj][m][n]; *(f32x4*)(out + off + bj * 128 + n * 16) = y;
;                         ss += (y[0] * y[0] + y[1] * y[1]) + (y[2] * y[2] + y[3] * y[3]);
;                         u32x2 w; w.x = cvt_pk_bf16(y[0], y[1]); w.y = cvt_pk_bf16(y[2], y[3]); if (xb) *(u32x2*)(xb + off + bj * 128 + n * 16) = w; }
;                 ss += __shfl_xor(ss, 16); ss += __shfl_xor(ss, 32);
;                 if (fq == 0) __hip_atomic_fetch_add(ssq + rz + rt + ai * 128 + m * 16, ss, __ATOMIC_RELAXED, __HIP_MEMORY_SCOPE_AGENT); }
	v_pk_add_f32 v[48:49], v[48:49], v[222:223]
	v_pk_add_f32 v[46:47], v[46:47], v[220:221]
	v_pk_add_f32 v[44:45], v[44:45], v[226:227]
	v_pk_add_f32 v[42:43], v[42:43], v[224:225]
	v_pk_add_f32 v[40:41], v[40:41], v[230:231]
	v_pk_add_f32 v[38:39], v[38:39], v[228:229]
	v_pk_add_f32 v[36:37], v[36:37], v[234:235]
	v_pk_add_f32 v[34:35], v[34:35], v[232:233]
	global_store_dwordx4 v148, v[46:49], s[8:9] offset:0 nt
	global_store_dwordx4 v148, v[42:45], s[8:9] offset:64 nt
	global_store_dwordx4 v148, v[38:41], s[8:9] offset:512 nt
	global_store_dwordx4 v148, v[34:37], s[8:9] offset:576 nt
	v_cvt_pk_bf16_f32 v220, v46, v47
	v_cvt_pk_bf16_f32 v221, v48, v49
	v_cvt_pk_bf16_f32 v224, v42, v43
	v_cvt_pk_bf16_f32 v225, v44, v45
	v_cvt_pk_bf16_f32 v228, v38, v39
	v_cvt_pk_bf16_f32 v229, v40, v41
	v_cvt_pk_bf16_f32 v232, v34, v35
	v_cvt_pk_bf16_f32 v233, v36, v37
	global_store_dwordx2 v147, v[220:221], s[36:37] offset:0
	global_store_dwordx2 v147, v[224:225], s[36:37] offset:32
	global_store_dwordx2 v147, v[228:229], s[36:37] offset:256
	global_store_dwordx2 v147, v[232:233], s[36:37] offset:288
	v_mul_f32_e32 v150, v47, v47
	v_mul_f32_e32 v151, v49, v49
	v_fmac_f32_e32 v150, v46, v46
	v_fmac_f32_e32 v151, v48, v48
	v_add_f32_e32 v150, v150, v151
	v_mul_f32_e32 v152, v43, v43
	v_mul_f32_e32 v153, v45, v45
	v_fmac_f32_e32 v152, v42, v42
	v_fmac_f32_e32 v153, v44, v44
	v_add_f32_e32 v152, v152, v153
	v_add_f32_e32 v150, v150, v152
	v_mul_f32_e32 v152, v39, v39
	v_mul_f32_e32 v153, v41, v41
	v_fmac_f32_e32 v152, v38, v38
	v_fmac_f32_e32 v153, v40, v40
	v_add_f32_e32 v152, v152, v153
	v_add_f32_e32 v150, v150, v152
	v_mul_f32_e32 v152, v35, v35
	v_mul_f32_e32 v153, v37, v37
	v_fmac_f32_e32 v152, v34, v34
	v_fmac_f32_e32 v153, v36, v36
	v_add_f32_e32 v152, v152, v153
	v_add_f32_e32 v150, v150, v152
	ds_bpermute_b32 v192, v1, v150
	s_waitcnt lgkmcnt(0)
	v_add_f32_e32 v150, v150, v192
	ds_bpermute_b32 v192, v142, v150
	v_add_u32_e32 v148, 0x20000, v148
	v_add_u32_e32 v147, 0x10000, v147
	s_and_saveexec_b64 s[12:13], s[6:7]
	s_waitcnt lgkmcnt(0)
	v_add_f32_e32 v150, v150, v192
	global_atomic_add_f32 v146, v150, s[70:71] offset:576
	s_mov_b64 exec, s[12:13]
	s_waitcnt vmcnt(23)
	v_pk_add_f32 v[32:33], v[32:33], v[170:171]
	v_pk_add_f32 v[30:31], v[30:31], v[168:169]
	v_pk_add_f32 v[28:29], v[28:29], v[174:175]
	v_pk_add_f32 v[26:27], v[26:27], v[172:173]
	v_pk_add_f32 v[24:25], v[24:25], v[178:179]
	v_pk_add_f32 v[22:23], v[22:23], v[176:177]
	v_pk_add_f32 v[20:21], v[20:21], v[182:183]
	v_pk_add_f32 v[18:19], v[18:19], v[180:181]
	global_store_dwordx4 v148, v[30:33], s[8:9] offset:0 nt
	global_store_dwordx4 v148, v[26:29], s[8:9] offset:64 nt
	global_store_dwordx4 v148, v[22:25], s[8:9] offset:512 nt
	global_store_dwordx4 v148, v[18:21], s[8:9] offset:576 nt
	v_cvt_pk_bf16_f32 v168, v30, v31
	v_cvt_pk_bf16_f32 v169, v32, v33
	v_cvt_pk_bf16_f32 v172, v26, v27
	v_cvt_pk_bf16_f32 v173, v28, v29
	v_cvt_pk_bf16_f32 v176, v22, v23
	v_cvt_pk_bf16_f32 v177, v24, v25
	v_cvt_pk_bf16_f32 v180, v18, v19
	v_cvt_pk_bf16_f32 v181, v20, v21
	global_store_dwordx2 v147, v[168:169], s[36:37] offset:0
	global_store_dwordx2 v147, v[172:173], s[36:37] offset:32
	global_store_dwordx2 v147, v[176:177], s[36:37] offset:256
	global_store_dwordx2 v147, v[180:181], s[36:37] offset:288
	v_mul_f32_e32 v150, v31, v31
	v_mul_f32_e32 v151, v33, v33
	v_fmac_f32_e32 v150, v30, v30
	v_fmac_f32_e32 v151, v32, v32
	v_add_f32_e32 v150, v150, v151
	v_mul_f32_e32 v152, v27, v27
	v_mul_f32_e32 v153, v29, v29
	v_fmac_f32_e32 v152, v26, v26
	v_fmac_f32_e32 v153, v28, v28
	v_add_f32_e32 v152, v152, v153
	v_add_f32_e32 v150, v150, v152
	v_mul_f32_e32 v152, v23, v23
	v_mul_f32_e32 v153, v25, v25
	v_fmac_f32_e32 v152, v22, v22
	v_fmac_f32_e32 v153, v24, v24
	v_add_f32_e32 v152, v152, v153
	v_add_f32_e32 v150, v150, v152
	v_mul_f32_e32 v152, v19, v19
	v_mul_f32_e32 v153, v21, v21
	v_fmac_f32_e32 v152, v18, v18
	v_fmac_f32_e32 v153, v20, v20
	v_add_f32_e32 v152, v152, v153
	v_add_f32_e32 v150, v150, v152
	ds_bpermute_b32 v192, v1, v150
	s_waitcnt lgkmcnt(0)
	v_add_f32_e32 v150, v150, v192
	ds_bpermute_b32 v192, v142, v150
	v_add_u32_e32 v148, 0x20000, v148
	v_add_u32_e32 v147, 0x10000, v147
	s_and_saveexec_b64 s[12:13], s[6:7]
	s_waitcnt lgkmcnt(0)
	v_add_f32_e32 v150, v150, v192
	global_atomic_add_f32 v146, v150, s[70:71] offset:640
	s_mov_b64 exec, s[12:13]
	s_waitcnt vmcnt(19)
	v_pk_add_f32 v[16:17], v[16:17], v[186:187]
	v_pk_add_f32 v[14:15], v[14:15], v[184:185]
	v_pk_add_f32 v[12:13], v[12:13], v[190:191]
	v_pk_add_f32 v[10:11], v[10:11], v[188:189]
	v_pk_add_f32 v[8:9], v[8:9], v[198:199]
	v_pk_add_f32 v[6:7], v[6:7], v[196:197]
	v_pk_add_f32 v[4:5], v[4:5], v[206:207]
	v_pk_add_f32 v[2:3], v[2:3], v[204:205]
	global_store_dwordx4 v148, v[14:17], s[8:9] offset:0 nt
	global_store_dwordx4 v148, v[10:13], s[8:9] offset:64 nt
	global_store_dwordx4 v148, v[6:9], s[8:9] offset:512 nt
	global_store_dwordx4 v148, v[2:5], s[8:9] offset:576 nt
	v_cvt_pk_bf16_f32 v184, v14, v15
	v_cvt_pk_bf16_f32 v185, v16, v17
	v_cvt_pk_bf16_f32 v188, v10, v11
	v_cvt_pk_bf16_f32 v189, v12, v13
	v_cvt_pk_bf16_f32 v196, v6, v7
	v_cvt_pk_bf16_f32 v197, v8, v9
	v_cvt_pk_bf16_f32 v204, v2, v3
	v_cvt_pk_bf16_f32 v205, v4, v5
	global_store_dwordx2 v147, v[184:185], s[36:37] offset:0
	global_store_dwordx2 v147, v[188:189], s[36:37] offset:32
	global_store_dwordx2 v147, v[196:197], s[36:37] offset:256
	global_store_dwordx2 v147, v[204:205], s[36:37] offset:288
	v_mul_f32_e32 v150, v15, v15
	v_mul_f32_e32 v151, v17, v17
	v_fmac_f32_e32 v150, v14, v14
	v_fmac_f32_e32 v151, v16, v16
	v_add_f32_e32 v150, v150, v151
	v_mul_f32_e32 v152, v11, v11
	v_mul_f32_e32 v153, v13, v13
	v_fmac_f32_e32 v152, v10, v10
	v_fmac_f32_e32 v153, v12, v12
	v_add_f32_e32 v152, v152, v153
	v_add_f32_e32 v150, v150, v152
	v_mul_f32_e32 v152, v7, v7
	v_mul_f32_e32 v153, v9, v9
	v_fmac_f32_e32 v152, v6, v6
	v_fmac_f32_e32 v153, v8, v8
	v_add_f32_e32 v152, v152, v153
	v_add_f32_e32 v150, v150, v152
	v_mul_f32_e32 v152, v3, v3
	v_mul_f32_e32 v153, v5, v5
	v_fmac_f32_e32 v152, v2, v2
	v_fmac_f32_e32 v153, v4, v4
	v_add_f32_e32 v152, v152, v153
	v_add_f32_e32 v150, v150, v152
	ds_bpermute_b32 v192, v1, v150
	s_waitcnt lgkmcnt(0)
	v_add_f32_e32 v150, v150, v192
	ds_bpermute_b32 v192, v142, v150
	s_and_saveexec_b64 s[12:13], s[6:7]
	s_waitcnt lgkmcnt(0)
	v_add_f32_e32 v150, v150, v192
	global_atomic_add_f32 v146, v150, s[70:71] offset:704
	s_mov_b64 exec, s[12:13]
	s_branch .Lres_done
; __device__ __forceinline__ unsigned cvt_pk_bf16(float lo, float hi) { f32x2 v = {lo, hi}; bf16x2_t b = __builtin_convertvector(v, bf16x2_t); return __builtin_bit_cast(unsigned, b); }
; template <int MODE> __device__ __forceinline__ void gemm_epilogue(f32x4 (&acc)[2][2][4][2], const GD& g, const pg8::Unit& u, int wr, int wc, int fr, int fq, LAS unsigned char* lds, const float (&rsv)[2][4]) {
;     ...
;         const float* base = g.f0; float* out = (float*)g.o0; bf16_t* xb = (bf16_t*)g.o1; float* ssq = (float*)g.f1;
;         const int col0 = u.pn * 256 + wc * 32 + 4 * fq; const int rz = (u.z / g.nz2) * g.ro1;
; #pragma unroll
;         for (int ai = 0; ai < 2; ++ai)
; #pragma unroll
;             for (int m = 0; m < 4; ++m) { const size_t off = (size_t)(rz + rt + ai * 128 + m * 16) * DM + col0;
;                 float ss = 0.f;
; #pragma unroll
;                 for (int bj = 0; bj < 2; ++bj)
; #pragma unroll
;                     for (int n = 0; n < 2; ++n) { const f32x4 bs = *(const f32x4*)(base + off + bj * 128 + n * 16); const f32x4 y = bs + acc[ai][bj][m][n]; *(f32x4*)(out + off + bj * 128 + n * 16) = y;
;                         ss += (y[0] * y[0] + y[1] * y[1]) + (y[2] * y[2] + y[3] * y[3]);
;                         u32x2 w; w.x = cvt_pk_bf16(y[0], y[1]); w.y = cvt_pk_bf16(y[2], y[3]); if (xb) *(u32x2*)(xb + off + bj * 128 + n * 16) = w; }
;                 ss += __shfl_xor(ss, 16); ss += __shfl_xor(ss, 32);
;                 if (fq == 0) __hip_atomic_fetch_add(ssq + rz + rt + ai * 128 + m * 16, ss, __ATOMIC_RELAXED, __HIP_MEMORY_SCOPE_AGENT); }
.Lres_noxb:
	global_load_dwordx4 v[168:171], v143, s[2:3] offset:0 nt
	global_load_dwordx4 v[172:175], v143, s[2:3] offset:64 nt
	global_load_dwordx4 v[176:179], v143, s[2:3] offset:512 nt
	global_load_dwordx4 v[180:183], v143, s[2:3] offset:576 nt
	v_add_u32_e32 v143, 0x20000, v143
	global_load_dwordx4 v[184:187], v143, s[2:3] offset:0 nt
	global_load_dwordx4 v[188:191], v143, s[2:3] offset:64 nt
	global_load_dwordx4 v[196:199], v143, s[2:3] offset:512 nt
	global_load_dwordx4 v[204:207], v143, s[2:3] offset:576 nt
	v_add_u32_e32 v143, 0x20000, v143
	global_load_dwordx4 v[220:223], v143, s[2:3] offset:0 nt
	global_load_dwordx4 v[224:227], v143, s[2:3] offset:64 nt
	global_load_dwordx4 v[228:231], v143, s[2:3] offset:512 nt
	global_load_dwordx4 v[232:235], v143, s[2:3] offset:576 nt
	s_waitcnt vmcnt(8)
	v_pk_add_f32 v[128:129], v[128:129], v[170:171]
	v_pk_add_f32 v[126:127], v[126:127], v[168:169]
	v_pk_add_f32 v[124:125], v[124:125], v[174:175]
	v_pk_add_f32 v[122:123], v[122:123], v[172:173]
	v_pk_add_f32 v[120:121], v[120:121], v[178:179]
	v_pk_add_f32 v[118:119], v[118:119], v[176:177]
	v_pk_add_f32 v[116:117], v[116:117], v[182:183]
	v_pk_add_f32 v[114:115], v[114:115], v[180:181]
	global_store_dwordx4 v148, v[126:129], s[8:9] offset:0 nt
	global_store_dwordx4 v148, v[122:125], s[8:9] offset:64 nt
	global_store_dwordx4 v148, v[118:121], s[8:9] offset:512 nt
	global_store_dwordx4 v148, v[114:117], s[8:9] offset:576 nt
	v_mul_f32_e32 v150, v127, v127
	v_mul_f32_e32 v151, v129, v129
	v_fmac_f32_e32 v150, v126, v126
	v_fmac_f32_e32 v151, v128, v128
	v_add_f32_e32 v150, v150, v151
	v_mul_f32_e32 v152, v123, v123
	v_mul_f32_e32 v153, v125, v125
	v_fmac_f32_e32 v152, v122, v122
	v_fmac_f32_e32 v153, v124, v124
	v_add_f32_e32 v152, v152, v153
	v_add_f32_e32 v150, v150, v152
	v_mul_f32_e32 v152, v119, v119
	v_mul_f32_e32 v153, v121, v121
	v_fmac_f32_e32 v152, v118, v118
	v_fmac_f32_e32 v153, v120, v120
	v_add_f32_e32 v152, v152, v153
	v_add_f32_e32 v150, v150, v152
	v_mul_f32_e32 v152, v115, v115
	v_mul_f32_e32 v153, v117, v117
	v_fmac_f32_e32 v152, v114, v114
	v_fmac_f32_e32 v153, v116, v116
	v_add_f32_e32 v152, v152, v153
	v_add_f32_e32 v150, v150, v152
	ds_bpermute_b32 v192, v1, v150
	v_add_u32_e32 v143, 0x20000, v143
	global_load_dwordx4 v[168:171], v143, s[2:3] offset:0 nt
	global_load_dwordx4 v[172:175], v143, s[2:3] offset:64 nt
	global_load_dwordx4 v[176:179], v143, s[2:3] offset:512 nt
	global_load_dwordx4 v[180:183], v143, s[2:3] offset:576 nt
	s_waitcnt lgkmcnt(0)
	v_add_f32_e32 v150, v150, v192
	ds_bpermute_b32 v192, v142, v150
	v_add_u32_e32 v148, 0x20000, v148
	s_and_saveexec_b64 s[12:13], s[6:7]
	s_waitcnt lgkmcnt(0)
	v_add_f32_e32 v150, v150, v192
	global_atomic_add_f32 v146, v150, s[70:71] offset:0
	s_mov_b64 exec, s[12:13]
	s_waitcnt vmcnt(13)
	v_pk_add_f32 v[112:113], v[112:113], v[186:187]
	v_pk_add_f32 v[110:111], v[110:111], v[184:185]
	v_pk_add_f32 v[108:109], v[108:109], v[190:191]
	v_pk_add_f32 v[106:107], v[106:107], v[188:189]
	v_pk_add_f32 v[104:105], v[104:105], v[198:199]
	v_pk_add_f32 v[102:103], v[102:103], v[196:197]
	v_pk_add_f32 v[100:101], v[100:101], v[206:207]
	v_pk_add_f32 v[98:99], v[98:99], v[204:205]
	global_store_dwordx4 v148, v[110:113], s[8:9] offset:0 nt
	global_store_dwordx4 v148, v[106:109], s[8:9] offset:64 nt
	global_store_dwordx4 v148, v[102:105], s[8:9] offset:512 nt
	global_store_dwordx4 v148, v[98:101], s[8:9] offset:576 nt
	v_mul_f32_e32 v150, v111, v111
	v_mul_f32_e32 v151, v113, v113
	v_fmac_f32_e32 v150, v110, v110
	v_fmac_f32_e32 v151, v112, v112
	v_add_f32_e32 v150, v150, v151
	v_mul_f32_e32 v152, v107, v107
	v_mul_f32_e32 v153, v109, v109
	v_fmac_f32_e32 v152, v106, v106
	v_fmac_f32_e32 v153, v108, v108
	v_add_f32_e32 v152, v152, v153
	v_add_f32_e32 v150, v150, v152
	v_mul_f32_e32 v152, v103, v103
	v_mul_f32_e32 v153, v105, v105
	v_fmac_f32_e32 v152, v102, v102
	v_fmac_f32_e32 v153, v104, v104
	v_add_f32_e32 v152, v152, v153
	v_add_f32_e32 v150, v150, v152
	v_mul_f32_e32 v152, v99, v99
	v_mul_f32_e32 v153, v101, v101
	v_fmac_f32_e32 v152, v98, v98
	v_fmac_f32_e32 v153, v100, v100
	v_add_f32_e32 v152, v152, v153
	v_add_f32_e32 v150, v150, v152
	ds_bpermute_b32 v192, v1, v150
	v_add_u32_e32 v143, 0xa0000, v143
	global_load_dwordx4 v[184:187], v143, s[2:3] offset:0 nt
	global_load_dwordx4 v[188:191], v143, s[2:3] offset:64 nt
	global_load_dwordx4 v[196:199], v143, s[2:3] offset:512 nt
	global_load_dwordx4 v[204:207], v143, s[2:3] offset:576 nt
	s_waitcnt lgkmcnt(0)
	v_add_f32_e32 v150, v150, v192
	ds_bpermute_b32 v192, v142, v150
	v_add_u32_e32 v148, 0x20000, v148
	s_and_saveexec_b64 s[12:13], s[6:7]
	s_waitcnt lgkmcnt(0)
	v_add_f32_e32 v150, v150, v192
	global_atomic_add_f32 v146, v150, s[70:71] offset:64
	s_mov_b64 exec, s[12:13]
	s_waitcnt vmcnt(18)
	v_pk_add_f32 v[96:97], v[96:97], v[222:223]
	v_pk_add_f32 v[94:95], v[94:95], v[220:221]
	v_pk_add_f32 v[92:93], v[92:93], v[226:227]
	v_pk_add_f32 v[90:91], v[90:91], v[224:225]
	v_pk_add_f32 v[88:89], v[88:89], v[230:231]
	v_pk_add_f32 v[86:87], v[86:87], v[228:229]
	v_pk_add_f32 v[84:85], v[84:85], v[234:235]
	v_pk_add_f32 v[82:83], v[82:83], v[232:233]
	global_store_dwordx4 v148, v[94:97], s[8:9] offset:0 nt
	global_store_dwordx4 v148, v[90:93], s[8:9] offset:64 nt
	global_store_dwordx4 v148, v[86:89], s[8:9] offset:512 nt
	global_store_dwordx4 v148, v[82:85], s[8:9] offset:576 nt
	v_mul_f32_e32 v150, v95, v95
	v_mul_f32_e32 v151, v97, v97
	v_fmac_f32_e32 v150, v94, v94
	v_fmac_f32_e32 v151, v96, v96
	v_add_f32_e32 v150, v150, v151
	v_mul_f32_e32 v152, v91, v91
	v_mul_f32_e32 v153, v93, v93
	v_fmac_f32_e32 v152, v90, v90
	v_fmac_f32_e32 v153, v92, v92
	v_add_f32_e32 v152, v152, v153
	v_add_f32_e32 v150, v150, v152
	v_mul_f32_e32 v152, v87, v87
	v_mul_f32_e32 v153, v89, v89
	v_fmac_f32_e32 v152, v86, v86
	v_fmac_f32_e32 v153, v88, v88
	v_add_f32_e32 v152, v152, v153
	v_add_f32_e32 v150, v150, v152
	v_mul_f32_e32 v152, v83, v83
	v_mul_f32_e32 v153, v85, v85
	v_fmac_f32_e32 v152, v82, v82
	v_fmac_f32_e32 v153, v84, v84
	v_add_f32_e32 v152, v152, v153
	v_add_f32_e32 v150, v150, v152
	ds_bpermute_b32 v192, v1, v150
	v_add_u32_e32 v143, 0x20000, v143
	global_load_dwordx4 v[220:223], v143, s[2:3] offset:0 nt
	global_load_dwordx4 v[224:227], v143, s[2:3] offset:64 nt
	global_load_dwordx4 v[228:231], v143, s[2:3] offset:512 nt
	global_load_dwordx4 v[232:235], v143, s[2:3] offset:576 nt
	s_waitcnt lgkmcnt(0)
; __device__ __forceinline__ unsigned cvt_pk_bf16(float lo, float hi) { f32x2 v = {lo, hi}; bf16x2_t b = __builtin_convertvector(v, bf16x2_t); return __builtin_bit_cast(unsigned, b); }
; template <int MODE> __device__ __forceinline__ void gemm_epilogue(f32x4 (&acc)[2][2][4][2], const GD& g, const pg8::Unit& u, int wr, int wc, int fr, int fq, LAS unsigned char* lds, const float (&rsv)[2][4]) {
;     ...
;     } else if constexpr (MODE == EP_RES) {
;         const float* base = g.f0; float* out = (float*)g.o0; bf16_t* xb = (bf16_t*)g.o1; float* ssq = (float*)g.f1;
;         const int col0 = u.pn * 256 + wc * 32 + 4 * fq; const int rz = (u.z / g.nz2) * g.ro1;
; #pragma unroll
;         for (int ai = 0; ai < 2; ++ai)
; #pragma unroll
;             for (int m = 0; m < 4; ++m) { const size_t off = (size_t)(rz + rt + ai * 128 + m * 16) * DM + col0;
;                 float ss = 0.f;
; #pragma unroll
;                 for (int bj = 0; bj < 2; ++bj)
; #pragma unroll
;                     for (int n = 0; n < 2; ++n) { const f32x4 bs = *(const f32x4*)(base + off + bj * 128 + n * 16); const f32x4 y = bs + acc[ai][bj][m][n]; *(f32x4*)(out + off + bj * 128 + n * 16) = y;
;                         ss += (y[0] * y[0] + y[1] * y[1]) + (y[2] * y[2] + y[3] * y[3]);
;                         u32x2 w; w.x = cvt_pk_bf16(y[0], y[1]); w.y = cvt_pk_bf16(y[2], y[3]); if (xb) *(u32x2*)(xb + off + bj * 128 + n * 16) = w; }
;                 ss += __shfl_xor(ss, 16); ss += __shfl_xor(ss, 32);
;                 if (fq == 0) __hip_atomic_fetch_add(ssq + rz + rt + ai * 128 + m * 16, ss, __ATOMIC_RELAXED, __HIP_MEMORY_SCOPE_AGENT); }
	v_add_f32_e32 v150, v150, v192
	ds_bpermute_b32 v192, v142, v150
	v_add_u32_e32 v148, 0x20000, v148
	s_and_saveexec_b64 s[12:13], s[6:7]
	s_waitcnt lgkmcnt(0)
	v_add_f32_e32 v150, v150, v192
	global_atomic_add_f32 v146, v150, s[70:71] offset:128
	s_mov_b64 exec, s[12:13]
	s_waitcnt vmcnt(19)
	v_pk_add_f32 v[80:81], v[80:81], v[170:171]
	v_pk_add_f32 v[78:79], v[78:79], v[168:169]
	v_pk_add_f32 v[76:77], v[76:77], v[174:175]
	v_pk_add_f32 v[74:75], v[74:75], v[172:173]
	v_pk_add_f32 v[72:73], v[72:73], v[178:179]
	v_pk_add_f32 v[70:71], v[70:71], v[176:177]
	v_pk_add_f32 v[68:69], v[68:69], v[182:183]
	v_pk_add_f32 v[66:67], v[66:67], v[180:181]
	global_store_dwordx4 v148, v[78:81], s[8:9] offset:0 nt
	global_store_dwordx4 v148, v[74:77], s[8:9] offset:64 nt
	global_store_dwordx4 v148, v[70:73], s[8:9] offset:512 nt
	global_store_dwordx4 v148, v[66:69], s[8:9] offset:576 nt
	v_mul_f32_e32 v150, v79, v79
	v_mul_f32_e32 v151, v81, v81
	v_fmac_f32_e32 v150, v78, v78
	v_fmac_f32_e32 v151, v80, v80
	v_add_f32_e32 v150, v150, v151
	v_mul_f32_e32 v152, v75, v75
	v_mul_f32_e32 v153, v77, v77
	v_fmac_f32_e32 v152, v74, v74
	v_fmac_f32_e32 v153, v76, v76
	v_add_f32_e32 v152, v152, v153
	v_add_f32_e32 v150, v150, v152
	v_mul_f32_e32 v152, v71, v71
	v_mul_f32_e32 v153, v73, v73
	v_fmac_f32_e32 v152, v70, v70
	v_fmac_f32_e32 v153, v72, v72
	v_add_f32_e32 v152, v152, v153
	v_add_f32_e32 v150, v150, v152
	v_mul_f32_e32 v152, v67, v67
	v_mul_f32_e32 v153, v69, v69
	v_fmac_f32_e32 v152, v66, v66
	v_fmac_f32_e32 v153, v68, v68
	v_add_f32_e32 v152, v152, v153
	v_add_f32_e32 v150, v150, v152
	ds_bpermute_b32 v192, v1, v150
	v_add_u32_e32 v143, 0x20000, v143
	global_load_dwordx4 v[168:171], v143, s[2:3] offset:0 nt
	global_load_dwordx4 v[172:175], v143, s[2:3] offset:64 nt
	global_load_dwordx4 v[176:179], v143, s[2:3] offset:512 nt
	global_load_dwordx4 v[180:183], v143, s[2:3] offset:576 nt
	s_waitcnt lgkmcnt(0)
	v_add_f32_e32 v150, v150, v192
	ds_bpermute_b32 v192, v142, v150
	v_add_u32_e32 v148, 0xa0000, v148
	s_and_saveexec_b64 s[12:13], s[6:7]
	s_waitcnt lgkmcnt(0)
	v_add_f32_e32 v150, v150, v192
	global_atomic_add_f32 v146, v150, s[70:71] offset:192
	s_mov_b64 exec, s[12:13]
	s_waitcnt vmcnt(19)
	v_pk_add_f32 v[64:65], v[64:65], v[186:187]
	v_pk_add_f32 v[62:63], v[62:63], v[184:185]
	v_pk_add_f32 v[60:61], v[60:61], v[190:191]
	v_pk_add_f32 v[58:59], v[58:59], v[188:189]
	v_pk_add_f32 v[56:57], v[56:57], v[198:199]
	v_pk_add_f32 v[54:55], v[54:55], v[196:197]
	v_pk_add_f32 v[52:53], v[52:53], v[206:207]
	v_pk_add_f32 v[50:51], v[50:51], v[204:205]
	global_store_dwordx4 v148, v[62:65], s[8:9] offset:0 nt
	global_store_dwordx4 v148, v[58:61], s[8:9] offset:64 nt
	global_store_dwordx4 v148, v[54:57], s[8:9] offset:512 nt
	global_store_dwordx4 v148, v[50:53], s[8:9] offset:576 nt
	v_mul_f32_e32 v150, v63, v63
	v_mul_f32_e32 v151, v65, v65
	v_fmac_f32_e32 v150, v62, v62
	v_fmac_f32_e32 v151, v64, v64
	v_add_f32_e32 v150, v150, v151
	v_mul_f32_e32 v152, v59, v59
	v_mul_f32_e32 v153, v61, v61
	v_fmac_f32_e32 v152, v58, v58
	v_fmac_f32_e32 v153, v60, v60
	v_add_f32_e32 v152, v152, v153
	v_add_f32_e32 v150, v150, v152
	v_mul_f32_e32 v152, v55, v55
	v_mul_f32_e32 v153, v57, v57
	v_fmac_f32_e32 v152, v54, v54
	v_fmac_f32_e32 v153, v56, v56
	v_add_f32_e32 v152, v152, v153
	v_add_f32_e32 v150, v150, v152
	v_mul_f32_e32 v152, v51, v51
	v_mul_f32_e32 v153, v53, v53
	v_fmac_f32_e32 v152, v50, v50
	v_fmac_f32_e32 v153, v52, v52
	v_add_f32_e32 v152, v152, v153
	v_add_f32_e32 v150, v150, v152
	ds_bpermute_b32 v192, v1, v150
	v_add_u32_e32 v143, 0x20000, v143
	global_load_dwordx4 v[184:187], v143, s[2:3] offset:0 nt
	global_load_dwordx4 v[188:191], v143, s[2:3] offset:64 nt
	global_load_dwordx4 v[196:199], v143, s[2:3] offset:512 nt
	global_load_dwordx4 v[204:207], v143, s[2:3] offset:576 nt
	s_waitcnt lgkmcnt(0)
	v_add_f32_e32 v150, v150, v192
	ds_bpermute_b32 v192, v142, v150
	v_add_u32_e32 v148, 0x20000, v148
	s_and_saveexec_b64 s[12:13], s[6:7]
	s_waitcnt lgkmcnt(0)
	v_add_f32_e32 v150, v150, v192
	global_atomic_add_f32 v146, v150, s[70:71] offset:512
	s_mov_b64 exec, s[12:13]
	s_waitcnt vmcnt(19)
; __device__ __forceinline__ unsigned cvt_pk_bf16(float lo, float hi) { f32x2 v = {lo, hi}; bf16x2_t b = __builtin_convertvector(v, bf16x2_t); return __builtin_bit_cast(unsigned, b); }
; template <int MODE> __device__ __forceinline__ void gemm_epilogue(f32x4 (&acc)[2][2][4][2], const GD& g, const pg8::Unit& u, int wr, int wc, int fr, int fq, LAS unsigned char* lds, const float (&rsv)[2][4]) {
;     ...
;     } else if constexpr (MODE == EP_RES) {
;         const float* base = g.f0; float* out = (float*)g.o0; bf16_t* xb = (bf16_t*)g.o1; float* ssq = (float*)g.f1;
;         const int col0 = u.pn * 256 + wc * 32 + 4 * fq; const int rz = (u.z / g.nz2) * g.ro1;
; #pragma unroll
;         for (int ai = 0; ai < 2; ++ai)
; #pragma unroll
;             for (int m = 0; m < 4; ++m) { const size_t off = (size_t)(rz + rt + ai * 128 + m * 16) * DM + col0;
;                 float ss = 0.f;
; #pragma unroll
;                 for (int bj = 0; bj < 2; ++bj)
; #pragma unroll
;                     for (int n = 0; n < 2; ++n) { const f32x4 bs = *(const f32x4*)(base + off + bj * 128 + n * 16); const f32x4 y = bs + acc[ai][bj][m][n]; *(f32x4*)(out + off + bj * 128 + n * 16) = y;
;                         ss += (y[0] * y[0] + y[1] * y[1]) + (y[2] * y[2] + y[3] * y[3]);
;                         u32x2 w; w.x = cvt_pk_bf16(y[0], y[1]); w.y = cvt_pk_bf16(y[2], y[3]); if (xb) *(u32x2*)(xb + off + bj * 128 + n * 16) = w; }
;                 ss += __shfl_xor(ss, 16); ss += __shfl_xor(ss, 32);
;                 if (fq == 0) __hip_atomic_fetch_add(ssq + rz + rt + ai * 128 + m * 16, ss, __ATOMIC_RELAXED, __HIP_MEMORY_SCOPE_AGENT); }
	v_pk_add_f32 v[48:49], v[48:49], v[222:223]
	v_pk_add_f32 v[46:47], v[46:47], v[220:221]
	v_pk_add_f32 v[44:45], v[44:45], v[226:227]
	v_pk_add_f32 v[42:43], v[42:43], v[224:225]
	v_pk_add_f32 v[40:41], v[40:41], v[230:231]
	v_pk_add_f32 v[38:39], v[38:39], v[228:229]
	v_pk_add_f32 v[36:37], v[36:37], v[234:235]
	v_pk_add_f32 v[34:35], v[34:35], v[232:233]
	global_store_dwordx4 v148, v[46:49], s[8:9] offset:0 nt
	global_store_dwordx4 v148, v[42:45], s[8:9] offset:64 nt
	global_store_dwordx4 v148, v[38:41], s[8:9] offset:512 nt
	global_store_dwordx4 v148, v[34:37], s[8:9] offset:576 nt
	v_mul_f32_e32 v150, v47, v47
	v_mul_f32_e32 v151, v49, v49
	v_fmac_f32_e32 v150, v46, v46
	v_fmac_f32_e32 v151, v48, v48
	v_add_f32_e32 v150, v150, v151
	v_mul_f32_e32 v152, v43, v43
	v_mul_f32_e32 v153, v45, v45
	v_fmac_f32_e32 v152, v42, v42
	v_fmac_f32_e32 v153, v44, v44
	v_add_f32_e32 v152, v152, v153
	v_add_f32_e32 v150, v150, v152
	v_mul_f32_e32 v152, v39, v39
	v_mul_f32_e32 v153, v41, v41
	v_fmac_f32_e32 v152, v38, v38
	v_fmac_f32_e32 v153, v40, v40
	v_add_f32_e32 v152, v152, v153
	v_add_f32_e32 v150, v150, v152
	v_mul_f32_e32 v152, v35, v35
	v_mul_f32_e32 v153, v37, v37
	v_fmac_f32_e32 v152, v34, v34
	v_fmac_f32_e32 v153, v36, v36
	v_add_f32_e32 v152, v152, v153
	v_add_f32_e32 v150, v150, v152
	ds_bpermute_b32 v192, v1, v150
	s_waitcnt lgkmcnt(0)
	v_add_f32_e32 v150, v150, v192
	ds_bpermute_b32 v192, v142, v150
	v_add_u32_e32 v148, 0x20000, v148
	s_and_saveexec_b64 s[12:13], s[6:7]
	s_waitcnt lgkmcnt(0)
	v_add_f32_e32 v150, v150, v192
	global_atomic_add_f32 v146, v150, s[70:71] offset:576
	s_mov_b64 exec, s[12:13]
	s_waitcnt vmcnt(15)
	v_pk_add_f32 v[32:33], v[32:33], v[170:171]
	v_pk_add_f32 v[30:31], v[30:31], v[168:169]
	v_pk_add_f32 v[28:29], v[28:29], v[174:175]
	v_pk_add_f32 v[26:27], v[26:27], v[172:173]
	v_pk_add_f32 v[24:25], v[24:25], v[178:179]
	v_pk_add_f32 v[22:23], v[22:23], v[176:177]
	v_pk_add_f32 v[20:21], v[20:21], v[182:183]
	v_pk_add_f32 v[18:19], v[18:19], v[180:181]
	global_store_dwordx4 v148, v[30:33], s[8:9] offset:0 nt
	global_store_dwordx4 v148, v[26:29], s[8:9] offset:64 nt
	global_store_dwordx4 v148, v[22:25], s[8:9] offset:512 nt
	global_store_dwordx4 v148, v[18:21], s[8:9] offset:576 nt
	v_mul_f32_e32 v150, v31, v31
	v_mul_f32_e32 v151, v33, v33
	v_fmac_f32_e32 v150, v30, v30
	v_fmac_f32_e32 v151, v32, v32
	v_add_f32_e32 v150, v150, v151
	v_mul_f32_e32 v152, v27, v27
	v_mul_f32_e32 v153, v29, v29
	v_fmac_f32_e32 v152, v26, v26
	v_fmac_f32_e32 v153, v28, v28
	v_add_f32_e32 v152, v152, v153
	v_add_f32_e32 v150, v150, v152
	v_mul_f32_e32 v152, v23, v23
	v_mul_f32_e32 v153, v25, v25
	v_fmac_f32_e32 v152, v22, v22
	v_fmac_f32_e32 v153, v24, v24
	v_add_f32_e32 v152, v152, v153
	v_add_f32_e32 v150, v150, v152
	v_mul_f32_e32 v152, v19, v19
	v_mul_f32_e32 v153, v21, v21
	v_fmac_f32_e32 v152, v18, v18
	v_fmac_f32_e32 v153, v20, v20
	v_add_f32_e32 v152, v152, v153
	v_add_f32_e32 v150, v150, v152
	ds_bpermute_b32 v192, v1, v150
	s_waitcnt lgkmcnt(0)
	v_add_f32_e32 v150, v150, v192
	ds_bpermute_b32 v192, v142, v150
	v_add_u32_e32 v148, 0x20000, v148
	s_and_saveexec_b64 s[12:13], s[6:7]
	s_waitcnt lgkmcnt(0)
	v_add_f32_e32 v150, v150, v192
	global_atomic_add_f32 v146, v150, s[70:71] offset:640
	s_mov_b64 exec, s[12:13]
	s_waitcnt vmcnt(11)
	v_pk_add_f32 v[16:17], v[16:17], v[186:187]
	v_pk_add_f32 v[14:15], v[14:15], v[184:185]
	v_pk_add_f32 v[12:13], v[12:13], v[190:191]
	v_pk_add_f32 v[10:11], v[10:11], v[188:189]
	v_pk_add_f32 v[8:9], v[8:9], v[198:199]
	v_pk_add_f32 v[6:7], v[6:7], v[196:197]
	v_pk_add_f32 v[4:5], v[4:5], v[206:207]
	v_pk_add_f32 v[2:3], v[2:3], v[204:205]
	global_store_dwordx4 v148, v[14:17], s[8:9] offset:0 nt
	global_store_dwordx4 v148, v[10:13], s[8:9] offset:64 nt
	global_store_dwordx4 v148, v[6:9], s[8:9] offset:512 nt
	global_store_dwordx4 v148, v[2:5], s[8:9] offset:576 nt
	v_mul_f32_e32 v150, v15, v15
	v_mul_f32_e32 v151, v17, v17
	v_fmac_f32_e32 v150, v14, v14
	v_fmac_f32_e32 v151, v16, v16
	v_add_f32_e32 v150, v150, v151
	v_mul_f32_e32 v152, v11, v11
	v_mul_f32_e32 v153, v13, v13
	v_fmac_f32_e32 v152, v10, v10
	v_fmac_f32_e32 v153, v12, v12
	v_add_f32_e32 v152, v152, v153
	v_add_f32_e32 v150, v150, v152
	v_mul_f32_e32 v152, v7, v7
	v_mul_f32_e32 v153, v9, v9
	v_fmac_f32_e32 v152, v6, v6
	v_fmac_f32_e32 v153, v8, v8
	v_add_f32_e32 v152, v152, v153
	v_add_f32_e32 v150, v150, v152
	v_mul_f32_e32 v152, v3, v3
	v_mul_f32_e32 v153, v5, v5
	v_fmac_f32_e32 v152, v2, v2
	v_fmac_f32_e32 v153, v4, v4
	v_add_f32_e32 v152, v152, v153
	v_add_f32_e32 v150, v150, v152
	ds_bpermute_b32 v192, v1, v150
	s_waitcnt lgkmcnt(0)
	v_add_f32_e32 v150, v150, v192
	ds_bpermute_b32 v192, v142, v150
	s_and_saveexec_b64 s[12:13], s[6:7]
	s_waitcnt lgkmcnt(0)
	v_add_f32_e32 v150, v150, v192
	global_atomic_add_f32 v146, v150, s[70:71] offset:704
	s_mov_b64 exec, s[12:13]

; __device__ __forceinline__ void final_rows(float* X, const float* gvec, const float* ssq, int nrows, int gw, int ngw, int lane) {
;     for (int row = gw; row < nrows; row += ngw) { const float r = rsqrtf(ssq[row] * (1.f / DM) + EPS);
;         f32x4* xr = (f32x4*)(X + (size_t)row * DM) + lane;
; #pragma unroll
;         for (int j = 0; j < 8; ++j) xr[64 * j] = xr[64 * j] * r * ((const f32x4*)gvec)[lane + 64 * j]; }
; }
.LBB0_644:
	global_load_dword v1, v0, s[6:7]
	global_load_dwordx4 v[24:27], v[12:13], off offset:-4096 nt
	global_load_dwordx4 v[28:31], v[12:13], off offset:-3072 nt
	global_load_dwordx4 v[32:35], v[12:13], off offset:-2048 nt
	global_load_dwordx4 v[36:39], v[12:13], off offset:-1024 nt
	global_load_dwordx4 v[40:43], v[12:13], off nt
	global_load_dwordx4 v[44:47], v[12:13], off offset:1024 nt
	global_load_dwordx4 v[48:51], v[12:13], off offset:2048 nt
	global_load_dwordx4 v[52:55], v[12:13], off offset:3072 nt
	s_add_u32 s6, s6, s2
	s_addc_u32 s7, s7, s3
	s_waitcnt vmcnt(8)
	v_fmamk_f32 v1, v1, 0x3a000000, v203
	v_cmp_gt_f32_e32 vcc, s80, v1
	v_mul_f32_e32 v14, 0x4b800000, v1
	s_nop 0
	v_cndmask_b32_e32 v1, v1, v14, vcc
	v_rsq_f32_e32 v1, v1
	s_nop 0
	v_mul_f32_e32 v14, 0x45800000, v1
	v_cndmask_b32_e32 v14, v1, v14, vcc
	s_waitcnt vmcnt(7)
	v_pk_mul_f32 v[24:25], v[24:25], v[14:15] op_sel_hi:[1,0]
	v_pk_mul_f32 v[26:27], v[26:27], v[14:15] op_sel_hi:[1,0]
	v_pk_mul_f32 v[24:25], v[24:25], v[56:57]
	v_pk_mul_f32 v[26:27], v[26:27], v[58:59]
	global_store_dwordx4 v[12:13], v[24:27], off offset:-4096 nt
	s_waitcnt vmcnt(7)
	v_pk_mul_f32 v[28:29], v[28:29], v[14:15] op_sel_hi:[1,0]
	v_pk_mul_f32 v[30:31], v[30:31], v[14:15] op_sel_hi:[1,0]
	v_pk_mul_f32 v[28:29], v[28:29], v[60:61]
	v_pk_mul_f32 v[30:31], v[30:31], v[62:63]
	global_store_dwordx4 v[12:13], v[28:31], off offset:-3072 nt
	s_waitcnt vmcnt(7)
	v_pk_mul_f32 v[32:33], v[32:33], v[14:15] op_sel_hi:[1,0]
	v_pk_mul_f32 v[34:35], v[34:35], v[14:15] op_sel_hi:[1,0]
	v_pk_mul_f32 v[32:33], v[32:33], v[64:65]
	v_pk_mul_f32 v[34:35], v[34:35], v[66:67]
	global_store_dwordx4 v[12:13], v[32:35], off offset:-2048 nt
	s_waitcnt vmcnt(7)
	v_pk_mul_f32 v[36:37], v[36:37], v[14:15] op_sel_hi:[1,0]
	v_pk_mul_f32 v[38:39], v[38:39], v[14:15] op_sel_hi:[1,0]
	v_pk_mul_f32 v[36:37], v[36:37], v[68:69]
	v_pk_mul_f32 v[38:39], v[38:39], v[70:71]
	global_store_dwordx4 v[12:13], v[36:39], off offset:-1024 nt
	s_waitcnt vmcnt(7)
	v_pk_mul_f32 v[40:41], v[40:41], v[14:15] op_sel_hi:[1,0]
	v_pk_mul_f32 v[42:43], v[42:43], v[14:15] op_sel_hi:[1,0]
	v_pk_mul_f32 v[40:41], v[40:41], v[72:73]
	v_pk_mul_f32 v[42:43], v[42:43], v[74:75]
	global_store_dwordx4 v[12:13], v[40:43], off nt
	s_waitcnt vmcnt(7)
	v_pk_mul_f32 v[44:45], v[44:45], v[14:15] op_sel_hi:[1,0]
	v_pk_mul_f32 v[46:47], v[46:47], v[14:15] op_sel_hi:[1,0]
	v_pk_mul_f32 v[44:45], v[44:45], v[76:77]
	v_pk_mul_f32 v[46:47], v[46:47], v[78:79]
	global_store_dwordx4 v[12:13], v[44:47], off offset:1024 nt
	s_waitcnt vmcnt(7)
	v_pk_mul_f32 v[48:49], v[48:49], v[14:15] op_sel_hi:[1,0]
	v_pk_mul_f32 v[50:51], v[50:51], v[14:15] op_sel_hi:[1,0]
	v_pk_mul_f32 v[48:49], v[48:49], v[80:81]
	v_pk_mul_f32 v[50:51], v[50:51], v[82:83]
	global_store_dwordx4 v[12:13], v[48:51], off offset:2048 nt
	s_waitcnt vmcnt(7)
	v_pk_mul_f32 v[52:53], v[52:53], v[14:15] op_sel_hi:[1,0]
	v_pk_mul_f32 v[54:55], v[54:55], v[14:15] op_sel_hi:[1,0]
	v_pk_mul_f32 v[52:53], v[52:53], v[84:85]
	v_pk_mul_f32 v[54:55], v[54:55], v[86:87]
	global_store_dwordx4 v[12:13], v[52:55], off offset:3072 nt
	v_lshl_add_u64 v[12:13], v[12:13], 0, s[26:27]
	s_add_i32 s0, s0, s70
	s_cmpk_lt_i32 s0, 0x4000
	s_cbranch_scc1 .LBB0_644
